# P0 prologue: gain-scaled weight items (w_in, ffn gate/up) issue their 16 weight + 16 gain loads per half-item together instead of one dependent round trip per element
# speedup vs baseline: 1.0183x; 1.0183x over previous
; #define LAS __attribute__((address_space(3)))
; __device__ __forceinline__ void tr_item(const float* __restrict__ W, int ldw, int k0, int ns0, bf16* WT, int K, int nd0, const float* __restrict__ gain, LAS float* scr, int lane) {
; #pragma unroll 16
;     for (int i = 0; i < 32; ++i) { const int kk = 2 * i + (lane >> 5); float w = W[(size_t)(k0 + kk) * ldw + ns0 + (lane & 31)]; if (gain) w *= gain[k0 + kk]; scr[kk * 33 + (lane & 31)] = w; }
; __device__ __forceinline__ void phase_prologue(KParams P, LAS unsigned char* lds, const int wave_sg) {
;     ...
;         if (r < I_IN) { const int kb = r / 160, nb = r % 160, nd0 = 32 * nb; int ns0 = nd0;
;             if (nd0 < 3072) { const int pn = nd0 >> 8, cl = nd0 & 255, bj = cl >> 7, wc = (cl >> 5) & 3; ns0 = 64 * (4 * pn + wc) + 32 * bj; }
;             tr_item(P->in[11], INW, 64 * kb, ns0, (bf16*)(ws + WS_WIN), DM, nd0, P->in[10], scr, lane); continue; }
.LBB0_26:
	v_cndmask_b32_e64 v138, 0, 1, s[10:11]
	v_cmp_ne_u32_e64 s[4:5], 1, v138
	v_lshl_add_u64 v[136:137], v[88:89], 0, s[0:1]
	global_load_dword v140, v[136:137], off
	v_lshl_add_u64 v[136:137], v[86:87], 0, s[0:1]
	global_load_dword v141, v[136:137], off
	v_lshl_add_u64 v[136:137], v[84:85], 0, s[0:1]
	global_load_dword v142, v[136:137], off
	v_lshl_add_u64 v[136:137], v[82:83], 0, s[0:1]
	global_load_dword v143, v[136:137], off
	v_lshl_add_u64 v[136:137], v[80:81], 0, s[0:1]
	global_load_dword v144, v[136:137], off
	v_lshl_add_u64 v[136:137], v[78:79], 0, s[0:1]
	global_load_dword v145, v[136:137], off
	v_lshl_add_u64 v[136:137], v[76:77], 0, s[0:1]
	global_load_dword v146, v[136:137], off
	v_lshl_add_u64 v[136:137], v[74:75], 0, s[0:1]
	global_load_dword v147, v[136:137], off
	v_lshl_add_u64 v[136:137], v[72:73], 0, s[0:1]
	global_load_dword v148, v[136:137], off
	v_lshl_add_u64 v[136:137], v[70:71], 0, s[0:1]
	global_load_dword v149, v[136:137], off
	v_lshl_add_u64 v[136:137], v[68:69], 0, s[0:1]
	global_load_dword v150, v[136:137], off
	v_lshl_add_u64 v[136:137], v[66:67], 0, s[0:1]
	global_load_dword v151, v[136:137], off
	v_lshl_add_u64 v[136:137], v[64:65], 0, s[0:1]
	global_load_dword v152, v[136:137], off
	v_lshl_add_u64 v[136:137], v[62:63], 0, s[0:1]
	global_load_dword v153, v[136:137], off
	v_lshl_add_u64 v[136:137], v[60:61], 0, s[0:1]
	global_load_dword v154, v[136:137], off
	v_lshl_add_u64 v[136:137], v[56:57], 0, s[0:1]
	global_load_dword v155, v[136:137], off
	s_andn2_b64 vcc, exec, s[10:11]
	s_cbranch_vccnz .Lp0g_in_nogain
	v_lshl_add_u64 v[136:137], s[8:9], 0, v[10:11]
	global_load_dword v160, v[136:137], off
	v_lshl_add_u64 v[136:137], s[8:9], 0, v[58:59]
	global_load_dword v161, v[136:137], off offset:8
	global_load_dword v162, v[136:137], off offset:16
	global_load_dword v163, v[136:137], off offset:24
	global_load_dword v164, v[136:137], off offset:32
	global_load_dword v165, v[136:137], off offset:40
	global_load_dword v166, v[136:137], off offset:48
	global_load_dword v167, v[136:137], off offset:56
	global_load_dword v168, v[136:137], off offset:64
	global_load_dword v169, v[136:137], off offset:72
	global_load_dword v170, v[136:137], off offset:80
	global_load_dword v171, v[136:137], off offset:88
	global_load_dword v172, v[136:137], off offset:96
	global_load_dword v173, v[136:137], off offset:104
	global_load_dword v174, v[136:137], off offset:112
	global_load_dword v175, v[136:137], off offset:120
	s_waitcnt vmcnt(0)
	v_mul_f32_e32 v140, v140, v160
	v_mul_f32_e32 v141, v141, v161
	v_mul_f32_e32 v142, v142, v162
	v_mul_f32_e32 v143, v143, v163
	v_mul_f32_e32 v144, v144, v164
	v_mul_f32_e32 v145, v145, v165
	v_mul_f32_e32 v146, v146, v166
	v_mul_f32_e32 v147, v147, v167
	v_mul_f32_e32 v148, v148, v168
	v_mul_f32_e32 v149, v149, v169
	v_mul_f32_e32 v150, v150, v170
	v_mul_f32_e32 v151, v151, v171
	v_mul_f32_e32 v152, v152, v172
	v_mul_f32_e32 v153, v153, v173
	v_mul_f32_e32 v154, v154, v174
	v_mul_f32_e32 v155, v155, v175
.Lp0g_in_nogain:
	s_waitcnt vmcnt(0)
	ds_write_b32 v92, v140
	ds_write_b32 v92, v141 offset:264
	ds_write_b32 v92, v142 offset:528
	ds_write_b32 v92, v143 offset:792
	ds_write_b32 v92, v144 offset:1056
	ds_write_b32 v92, v145 offset:1320
	ds_write_b32 v92, v146 offset:1584
	ds_write_b32 v92, v147 offset:1848
	ds_write_b32 v92, v148 offset:2112
	ds_write_b32 v92, v149 offset:2376
	ds_write_b32 v92, v150 offset:2640
	ds_write_b32 v92, v151 offset:2904
	ds_write_b32 v92, v152 offset:3168
	ds_write_b32 v92, v153 offset:3432
	ds_write_b32 v92, v154 offset:3696
	ds_write_b32 v92, v155 offset:3960
	s_add_u32 s0, s0, 0xa0000
	s_addc_u32 s1, s1, 0
	s_add_u32 s8, s8, 0x80
	s_addc_u32 s9, s9, 0
	v_add_u32_e32 v92, 0x1080, v92
	s_cmp_lg_u32 s0, 0x140000
	s_cbranch_scc1 .LBB0_26
	s_branch .LBB0_59

; #define LAS __attribute__((address_space(3)))
; __device__ __forceinline__ void tr_item(const float* __restrict__ W, int ldw, int k0, int ns0, bf16* WT, int K, int nd0, const float* __restrict__ gain, LAS float* scr, int lane) {
; #pragma unroll 16
;     for (int i = 0; i < 32; ++i) { const int kk = 2 * i + (lane >> 5); float w = W[(size_t)(k0 + kk) * ldw + ns0 + (lane & 31)]; if (gain) w *= gain[k0 + kk]; scr[kk * 33 + (lane & 31)] = w; }
; __device__ __forceinline__ void phase_prologue(KParams P, LAS unsigned char* lds, const int wave_sg) {
;     ...
;         if (r < 2 * I_GU) { const int L = r / I_GU; r -= L * I_GU; const int kb = r / 176, nb = r % 176, nd0 = 32 * nb, pn = nd0 >> 8, bj = (nd0 >> 7) & 1, c = nd0 & 127;
;             const float* W = P->in[L ? (bj ? 22 : 21) : (bj ? 8 : 7)];
;             tr_item(W, DFF, 64 * kb, 128 * pn + c, (bf16*)(ws + (L ? WS_W2GU : WS_W1GU)), DM, nd0, P->in[L ? 20 : 6], scr, lane); continue; }
.LBB0_66:
	v_cndmask_b32_e64 v138, 0, 1, s[24:25]
	v_cmp_ne_u32_e64 s[4:5], 1, v138
	v_lshl_add_u64 v[136:137], v[90:91], 0, s[18:19]
	global_load_dword v140, v[136:137], off
	v_lshl_add_u64 v[136:137], v[86:87], 0, s[18:19]
	global_load_dword v141, v[136:137], off
	v_lshl_add_u64 v[136:137], v[84:85], 0, s[18:19]
	global_load_dword v142, v[136:137], off
	v_lshl_add_u64 v[136:137], v[82:83], 0, s[18:19]
	global_load_dword v143, v[136:137], off
	v_lshl_add_u64 v[136:137], v[80:81], 0, s[18:19]
	global_load_dword v144, v[136:137], off
	v_lshl_add_u64 v[136:137], v[78:79], 0, s[18:19]
	global_load_dword v145, v[136:137], off
	v_lshl_add_u64 v[136:137], v[76:77], 0, s[18:19]
	global_load_dword v146, v[136:137], off
	v_lshl_add_u64 v[136:137], v[74:75], 0, s[18:19]
	global_load_dword v147, v[136:137], off
	v_lshl_add_u64 v[136:137], v[72:73], 0, s[18:19]
	global_load_dword v148, v[136:137], off
	v_lshl_add_u64 v[136:137], v[70:71], 0, s[18:19]
	global_load_dword v149, v[136:137], off
	v_lshl_add_u64 v[136:137], v[68:69], 0, s[18:19]
	global_load_dword v150, v[136:137], off
	v_lshl_add_u64 v[136:137], v[66:67], 0, s[18:19]
	global_load_dword v151, v[136:137], off
	v_lshl_add_u64 v[136:137], v[64:65], 0, s[18:19]
	global_load_dword v152, v[136:137], off
	v_lshl_add_u64 v[136:137], v[62:63], 0, s[18:19]
	global_load_dword v153, v[136:137], off
	v_lshl_add_u64 v[136:137], v[60:61], 0, s[18:19]
	global_load_dword v154, v[136:137], off
	v_lshl_add_u64 v[136:137], v[56:57], 0, s[18:19]
	global_load_dword v155, v[136:137], off
	s_andn2_b64 vcc, exec, s[24:25]
	s_cbranch_vccnz .Lp0g_gu_nogain
	v_lshl_add_u64 v[136:137], s[10:11], 0, v[88:89]
	global_load_dword v160, v[136:137], off
	v_lshl_add_u64 v[136:137], s[10:11], 0, v[58:59]
	global_load_dword v161, v[136:137], off offset:8
	global_load_dword v162, v[136:137], off offset:16
	global_load_dword v163, v[136:137], off offset:24
	global_load_dword v164, v[136:137], off offset:32
	global_load_dword v165, v[136:137], off offset:40
	global_load_dword v166, v[136:137], off offset:48
	global_load_dword v167, v[136:137], off offset:56
	global_load_dword v168, v[136:137], off offset:64
	global_load_dword v169, v[136:137], off offset:72
	global_load_dword v170, v[136:137], off offset:80
	global_load_dword v171, v[136:137], off offset:88
	global_load_dword v172, v[136:137], off offset:96
	global_load_dword v173, v[136:137], off offset:104
	global_load_dword v174, v[136:137], off offset:112
	global_load_dword v175, v[136:137], off offset:120
	s_waitcnt vmcnt(0)
	v_mul_f32_e32 v140, v140, v160
	v_mul_f32_e32 v141, v141, v161
	v_mul_f32_e32 v142, v142, v162
	v_mul_f32_e32 v143, v143, v163
	v_mul_f32_e32 v144, v144, v164
	v_mul_f32_e32 v145, v145, v165
	v_mul_f32_e32 v146, v146, v166
	v_mul_f32_e32 v147, v147, v167
	v_mul_f32_e32 v148, v148, v168
	v_mul_f32_e32 v149, v149, v169
	v_mul_f32_e32 v150, v150, v170
	v_mul_f32_e32 v151, v151, v171
	v_mul_f32_e32 v152, v152, v172
	v_mul_f32_e32 v153, v153, v173
	v_mul_f32_e32 v154, v154, v174
	v_mul_f32_e32 v155, v155, v175
.Lp0g_gu_nogain:
	s_waitcnt vmcnt(0)
	ds_write_b32 v10, v140
	ds_write_b32 v10, v141 offset:264
	ds_write_b32 v10, v142 offset:528
	ds_write_b32 v10, v143 offset:792
	ds_write_b32 v10, v144 offset:1056
	ds_write_b32 v10, v145 offset:1320
	ds_write_b32 v10, v146 offset:1584
	ds_write_b32 v10, v147 offset:1848
	ds_write_b32 v10, v148 offset:2112
	ds_write_b32 v10, v149 offset:2376
	ds_write_b32 v10, v150 offset:2640
	ds_write_b32 v10, v151 offset:2904
	ds_write_b32 v10, v152 offset:3168
	ds_write_b32 v10, v153 offset:3432
	ds_write_b32 v10, v154 offset:3696
	ds_write_b32 v10, v155 offset:3960
	s_add_u32 s18, s18, 0x58000
	s_addc_u32 s19, s19, 0
	s_add_u32 s10, s10, 0x80
	s_addc_u32 s11, s11, 0
	v_add_u32_e32 v10, 0x1080, v10
	s_cmp_lg_u32 s18, 0xb0000
	s_cbranch_scc1 .LBB0_66
	s_branch .LBB0_7
